# attention: V tile LDS layout permuted for ds_read_b128 fragments, rare rescale/general paths out of line, packed-f32 row-sum, fewer counted LDS waits
# baseline (speedup 1.0000x reference)
; template <int MODE>
; __device__ __forceinline__ void attn_phase(const Args& a, bool do_ctx, LAS unsigned char* lds, const int wid_s) {
;     ...
;         const unsigned skn = (unsigned)((tid >> 3) * KROW + (tid & 7) * 16);
;         const unsigned skr = (unsigned)(((tid & 255) >> 2) * KROW + 128 + (tid & 3) * 16);
;         const unsigned svt = (unsigned)((tid >> 3) * VROW + (tid & 7) * 16);
.LBB0_420:
	s_barrier
	v_mbcnt_lo_u32_b32 v1, -1, 0
	v_mbcnt_hi_u32_b32 v1, -1, v1
	v_readlane_b32 s0, v249, 8
	v_and_b32_e32 v5, 31, v1
	v_readlane_b32 s2, v249, 38
	v_add_u32_e32 v3, s0, v1
	v_and_b32_e32 v4, 63, v1
	v_bfe_u32 v6, v1, 5, 1
	v_or_b32_e32 v158, s2, v5
	v_and_b32_e32 v7, 7, v1
	v_lshlrev_b32_e32 v1, 4, v1
	v_readlane_b32 s2, v249, 50
	v_and_b32_e32 v132, 48, v1
	v_mov_b32_e32 v133, v201
	v_readlane_b32 s3, v249, 51
	v_readlane_b32 s0, v250, 5
	v_lshlrev_b32_e32 v136, 4, v7
	v_lshl_add_u64 v[134:135], s[2:3], 0, v[132:133]
	v_readlane_b32 s2, v249, 58
	v_mov_b32_e32 v137, v201
	v_readlane_b32 s3, v249, 59
	v_readlane_b32 s1, v250, 6
	v_ashrrev_i32_e32 v159, 3, v3
	v_lshl_add_u64 v[138:139], s[2:3], 0, v[136:137]
	s_movk_i32 s3, 0xd0
	s_movk_i32 s2, 0xffb8
	s_and_b64 s[0:1], s[0:1], exec
	v_lshlrev_b32_e32 v0, 3, v6
	v_bfe_u32 v160, v3, 2, 6
	v_mul_lo_u32 v1, v159, s3
	v_mul_lo_u32 v161, v159, s2
	s_movk_i32 s2, 0x100
	v_lshlrev_b32_e32 v4, 2, v4
	s_movk_i32 s0, 0x420
	s_mov_b32 s1, 0
	v_lshlrev_b32_e32 v2, 3, v7
	v_add3_u32 v162, v1, v136, 0
	v_cmp_gt_i32_e64 s[6:7], s2, v3
	v_mad_u32_u24 v1, v160, s3, v132
	v_mad_u32_u24 v3, v5, s3, 0
	v_and_b32_e32 v251, 6, v7
	v_lshlrev_b32_e32 v251, 4, v251
	v_and_b32_e32 v240, 1, v7
	v_lshl_add_u32 v251, v240, 3, v251
	s_movk_i32 s86, 0x90
	v_mad_u32_u24 v251, v159, s86, v251
	v_add_u32_e32 v251, 0x8c00, v251
	v_lshlrev_b32_e32 v7, 4, v6
	v_xor_b32_e32 v163, 0x80, v4
	v_add_u32_e32 v8, 0, v0
	v_mul_u32_u24_e32 v240, 0x90, v5
	v_lshl_add_u32 v240, v6, 4, v240
	v_mul_u32_u24_e32 v5, 0x88, v5
	v_lshlrev_b32_e32 v4, 2, v6
	s_cselect_b32 s0, s0, 0x400
	v_lshlrev_b32_e32 v200, 1, v0
	v_lshlrev_b32_e32 v140, 1, v2
	v_lshlrev_b32_e32 v142, 1, v4
	v_add_u32_e32 v164, 0, v1
	v_add_u32_e32 v165, v3, v7
	v_add_u32_e32 v166, v8, v5
	s_mov_b32 s24, s1
	s_branch .LBB0_423

; #define ATT_LOADK(rk, rr, kt_) do { if (MODE == 3 && (kt_) > 1) break; rk = *(const u32x4*)(gkn + (size_t)(kt_) * 64 * 512); rr = *(const u32x4*)(gkr + (size_t)(kt_) * 64 * 32); } while (0)
; #define ATT_LOADV(rv, kt_) do { if (MODE == 3 && (kt_) > 1) break; rv = *(const u32x4*)(gvt + (size_t)(kt_) * 64); } while (0)
; #define ATT_WRITEK(rk, rr, buf) do { LAS unsigned char* nb_ = lds + (buf) * KBUF; *(LAS u32x4*)(nb_ + skn) = rk; if (tid < 256) *(LAS u32x4*)(nb_ + skr) = rr; } while (0)
; #define ATT_WRITEV(rv, buf) do { LAS u32x2* p_ = (LAS u32x2*)(ldsv + (buf) * VBUF + svt); u32x2 lo_ = {rv[0], rv[1]}, hi_ = {rv[2], rv[3]}; p_[0] = lo_; p_[1] = hi_; } while (0)
; template <int MODE>
; __device__ __forceinline__ void attn_phase(const Args& a, bool do_ctx, LAS unsigned char* lds, const int wid_s) {
;     ...
;         ATT_LOADK(kK, kR, 0); ATT_LOADV(vV, 0);
;         ATT_WRITEK(kK, kR, 0); ATT_WRITEV(vV, 0);
;         ATT_LOADK(kK, kR, 1);
;         ATT_WRITEK(kK, kR, 1);
.LBB0_431:
	s_or_b64 exec, exec, s[2:3]
	s_movk_i32 s2, 0x6800
	v_add_u32_e32 v141, 0xffffdc00, v251
	s_waitcnt vmcnt(0)
	ds_write2_b64 v141, v[0:1], v[2:3] offset1:2
	v_add_co_u32_e32 v0, vcc, 0x10000, v4
	s_nop 1
	v_addc_co_u32_e32 v1, vcc, 0, v5, vcc
	global_load_dwordx4 v[120:123], v[0:1], off
	v_add_co_u32_e32 v0, vcc, 0x1000, v6
	s_waitcnt vmcnt(0)
	ds_write_b128 v162, v[120:123] offset:13312
	v_addc_co_u32_e32 v1, vcc, 0, v7, vcc
	global_load_dwordx4 v[124:127], v[0:1], off
	s_and_saveexec_b64 s[2:3], s[6:7]
	s_cbranch_execz .LBB0_433
	s_waitcnt vmcnt(0)
	ds_write_b128 v164, v[124:127] offset:13440

; #define LAS __attribute__((address_space(3)))
; __device__ __forceinline__ float shx32(float v, int lane) { return __int_as_float(__builtin_amdgcn_ds_bpermute((lane ^ 32) << 2, __float_as_int(v))); }
; __device__ __forceinline__ unsigned pk_bf16(float lo, float hi) { unsigned r; asm("v_cvt_pk_bf16_f32 %0, %1, %2" : "=v"(r) : "v"(lo), "v"(hi)); return r; }
; template <int MODE>
; __device__ __forceinline__ void attn_pv(const LAS unsigned char* vb_, f32x16 (&st)[2], f32x16 (&ot)[2], float& mrun, float& lsum, const int ql, const int hf, const int lane) {
;     if (MODE != 1) {
;     float mx = max3f(st[0][0], st[1][0], st[0][1]), my = max3f(st[1][1], st[0][2], st[1][2]);
; #pragma unroll
;     for (int i = 3; i < 15; i += 2) { mx = max3f(mx, st[0][i], st[1][i]); my = max3f(my, st[0][i + 1], st[1][i + 1]); }
;     mx = max3f(mx, st[0][15], st[1][15]); mx = max3f(mx, my, my);
;     if (__builtin_amdgcn_ballot_w64(mx > mrun + 8.0f) != 0ull) {
;         mx = fmaxf(mx, shx32(mx, lane));
;         const float mnew = (mx > mrun + 8.0f) ? mx : mrun;
;         const float alpha = fexp2(mrun - mnew);
;         mrun = mnew; lsum *= alpha;
; #pragma unroll
;         for (int i = 0; i < 16; ++i) { ot[0][i] *= alpha; ot[1][i] *= alpha; }
;     }
;     float ps = 0.f;
; #pragma unroll
;     for (int kb = 0; kb < 2; ++kb)
; #pragma unroll
;         for (int i = 0; i < 16; ++i) { const float p = fexp2(st[kb][i] - mrun); st[kb][i] = p; ps += p; }
;     lsum += ps;
;     } else lsum += st[0][0];
; #pragma unroll
;     for (int kb = 0; kb < 2; ++kb)
; #pragma unroll
;         for (int sI = 0; sI < 2; ++sI) {
;             u32x4 pw = {pk_bf16(st[kb][8 * sI + 0], st[kb][8 * sI + 1]), pk_bf16(st[kb][8 * sI + 2], st[kb][8 * sI + 3]),
;                         pk_bf16(st[kb][8 * sI + 4], st[kb][8 * sI + 5]), pk_bf16(st[kb][8 * sI + 6], st[kb][8 * sI + 7])};
;             const bf16x8 pf = __builtin_bit_cast(bf16x8, pw);
; #pragma unroll
;             for (int db = 0; db < 2; ++db) {
;                 const LAS unsigned char* vp = vb_ + (db * 32 + ql) * VROW + (kb * 32 + 16 * sI + 4 * hf) * 2;
;                 const u32x2 v0 = *(const LAS u32x2*)vp, v1 = *(const LAS u32x2*)(vp + 16);
;                 u32x4 vw = {v0[0], v0[1], v1[0], v1[1]};
;                 ot[db] = att_mma<MODE>(__builtin_bit_cast(bf16x8, vw), pf, ot[db]);
;             }
;         }
; }
.LBB0_437:
	global_load_dwordx4 v[128:131], v150, s[84:85] offset:128
	ds_read_b128 v[64:67], v165 offset:13312
	ds_read_b128 v[168:171], v165 offset:13344
	ds_read_b128 v[68:71], v165 offset:19968
	ds_read_b128 v[172:175], v165 offset:20000
	ds_read_b128 v[176:179], v165 offset:13376
	ds_read_b128 v[180:183], v165 offset:13408
	ds_read_b128 v[184:187], v165 offset:20032
	ds_read_b128 v[188:191], v165 offset:20064
	ds_read_b128 v[206:209], v240 offset:31232
	ds_read_b128 v[210:213], v240 offset:26624
	ds_read_b128 v[214:217], v240 offset:31264
	ds_read_b128 v[218:221], v240 offset:26656
	ds_read_b128 v[222:225], v240 offset:31296
	ds_read_b128 v[226:229], v240 offset:26688
	ds_read_b128 v[236:239], v240 offset:26720
	v_max3_f32 v156, v48, v32, v49
	v_max3_f32 v157, v33, v50, v34
	v_max3_f32 v156, v156, v51, v35
	v_max3_f32 v157, v157, v52, v36
	v_max3_f32 v156, v156, v53, v37
	v_max3_f32 v157, v157, v54, v38
	v_max3_f32 v156, v156, v55, v39
	v_max3_f32 v157, v157, v56, v40
	v_max3_f32 v156, v156, v57, v41
	v_max3_f32 v157, v157, v58, v42
	v_max3_f32 v156, v156, v59, v43
	v_max3_f32 v157, v157, v60, v44
	v_max3_f32 v156, v156, v61, v45
	v_max3_f32 v157, v157, v62, v46
	v_max3_f32 v156, v156, v63, v47
	v_max3_f32 v157, v156, v157, v157
	v_add_f32_e32 v156, 0x41000000, v143
	v_cmp_gt_f32_e32 vcc, v157, v156
	s_cbranch_vccnz .Latt_e_nors_resc
.Latt_e_nors:
	s_cmp_eq_u32 s90, 0
	s_cbranch_scc1 .Latt_e_nors_gen
	v_exp_f32_e32 v48, v48
	v_exp_f32_e32 v49, v49
	v_exp_f32_e32 v50, v50
	v_exp_f32_e32 v51, v51
	v_exp_f32_e32 v52, v52
	v_exp_f32_e32 v53, v53
	v_exp_f32_e32 v54, v54
	v_exp_f32_e32 v55, v55
	s_waitcnt lgkmcnt(11)
	v_mfma_f32_32x32x16_bf16 v[80:95], v[64:67], v[112:115], 0
	v_cvt_pk_bf16_f32 v152, v48, v49
	v_cvt_pk_bf16_f32 v153, v50, v51
	v_cvt_pk_bf16_f32 v154, v52, v53
	v_cvt_pk_bf16_f32 v155, v54, v55
	v_mfma_f32_32x32x16_bf16 v[64:79], v[68:71], v[112:115], 0
	v_pk_add_f32 v[230:231], v[48:49], v[50:51]
	v_pk_add_f32 v[230:231], v[230:231], v[52:53]
	v_pk_add_f32 v[230:231], v[230:231], v[54:55]
	v_mfma_f32_32x32x16_bf16 v[80:95], v[168:171], v[96:99], v[80:95]
	v_mfma_f32_32x32x16_bf16 v[64:79], v[172:175], v[96:99], v[64:79]
	ds_read_b128 v[168:171], v165 offset:13440
	ds_read_b128 v[172:175], v165 offset:13472
	ds_read_b128 v[192:195], v165 offset:20096
	ds_read_b128 v[196:199], v165 offset:20128
	v_exp_f32_e32 v56, v56
	v_exp_f32_e32 v57, v57
	v_exp_f32_e32 v58, v58
	v_exp_f32_e32 v59, v59
	s_waitcnt lgkmcnt(11)
	v_mfma_f32_32x32x16_bf16 v[80:95], v[176:179], v[100:103], v[80:95]
	ds_read_b128 a[0:3], v240 offset:31328
	v_exp_f32_e32 v60, v60
	v_exp_f32_e32 v61, v61
	v_exp_f32_e32 v62, v62
	v_exp_f32_e32 v63, v63
	v_mfma_f32_32x32x16_bf16 v[64:79], v[184:187], v[100:103], v[64:79]
	v_mfma_f32_32x32x16_bf16 v[80:95], v[180:183], v[104:107], v[80:95]
	v_cvt_pk_bf16_f32 v48, v56, v57
	v_cvt_pk_bf16_f32 v49, v58, v59
	v_cvt_pk_bf16_f32 v50, v60, v61
	v_cvt_pk_bf16_f32 v51, v62, v63
	v_mfma_f32_32x32x16_bf16 v[64:79], v[188:191], v[104:107], v[64:79]
	s_waitcnt lgkmcnt(10)
	v_mfma_f32_32x32x16_bf16 v[16:31], v[206:209], v[152:155], v[16:31]
	v_pk_add_f32 v[230:231], v[230:231], v[56:57]
	v_pk_add_f32 v[230:231], v[230:231], v[58:59]
	v_pk_add_f32 v[230:231], v[230:231], v[60:61]
	v_pk_add_f32 v[230:231], v[230:231], v[62:63]
	v_mfma_f32_32x32x16_bf16 v[0:15], v[210:213], v[152:155], v[0:15]
	s_waitcnt lgkmcnt(1)
	v_mfma_f32_32x32x16_bf16 v[80:95], v[168:171], v[108:111], v[80:95]
	v_exp_f32_e32 v32, v32
	v_exp_f32_e32 v33, v33
	v_exp_f32_e32 v34, v34
	v_exp_f32_e32 v35, v35
	v_mfma_f32_32x32x16_bf16 v[16:31], v[214:217], v[48:51], v[16:31]
	v_exp_f32_e32 v36, v36
	v_exp_f32_e32 v37, v37
	v_exp_f32_e32 v38, v38
	v_exp_f32_e32 v39, v39
	v_mfma_f32_32x32x16_bf16 v[0:15], v[218:221], v[48:51], v[0:15]
	v_cvt_pk_bf16_f32 v152, v32, v33
	v_cvt_pk_bf16_f32 v153, v34, v35
	v_cvt_pk_bf16_f32 v154, v36, v37
	v_cvt_pk_bf16_f32 v155, v38, v39
	v_mfma_f32_32x32x16_bf16 v[64:79], v[192:195], v[108:111], v[64:79]
	v_pk_add_f32 v[230:231], v[230:231], v[32:33]
	v_pk_add_f32 v[230:231], v[230:231], v[34:35]
	v_pk_add_f32 v[230:231], v[230:231], v[36:37]
	v_pk_add_f32 v[230:231], v[230:231], v[38:39]
	v_mfma_f32_32x32x16_bf16 v[80:95], v[172:175], v[116:119], v[80:95]
	v_mfma_f32_32x32x16_bf16 v[64:79], v[196:199], v[116:119], v[64:79]
	s_andn2_b64 vcc, exec, s[10:11]
	s_cbranch_vccnz .Latt_wskip_e1
	s_waitcnt vmcnt(2)
	ds_write_b128 v162, v[120:123]
	s_and_saveexec_b64 s[2:3], s[6:7]
	s_cbranch_execz .Latt_wk_e1
	s_waitcnt vmcnt(1)
	ds_write_b128 v164, v[124:127] offset:128

; #define LAS __attribute__((address_space(3)))
; __device__ __forceinline__ unsigned pk_bf16(float lo, float hi) { unsigned r; asm("v_cvt_pk_bf16_f32 %0, %1, %2" : "=v"(r) : "v"(lo), "v"(hi)); return r; }
; __device__ __forceinline__ float fexp2(float x) { return __builtin_amdgcn_exp2f(x); }
; #define ATT_WRITEV(rv, buf) do { LAS u32x2* p_ = (LAS u32x2*)(ldsv + (buf) * VBUF + svt); u32x2 lo_ = {rv[0], rv[1]}, hi_ = {rv[2], rv[3]}; p_[0] = lo_; p_[1] = hi_; } while (0)
; template <int MODE>
; __device__ __forceinline__ void attn_pv(const LAS unsigned char* vb_, f32x16 (&st)[2], f32x16 (&ot)[2], float& mrun, float& lsum, const int ql, const int hf, const int lane) {
;     ...
;     float ps = 0.f;
; #pragma unroll
;     for (int kb = 0; kb < 2; ++kb)
; #pragma unroll
;         for (int i = 0; i < 16; ++i) { const float p = fexp2(st[kb][i] - mrun); st[kb][i] = p; ps += p; }
;     lsum += ps;
;     } else lsum += st[0][0];
; #pragma unroll
;     for (int kb = 0; kb < 2; ++kb)
; #pragma unroll
;         for (int sI = 0; sI < 2; ++sI) {
;             u32x4 pw = {pk_bf16(st[kb][8 * sI + 0], st[kb][8 * sI + 1]), pk_bf16(st[kb][8 * sI + 2], st[kb][8 * sI + 3]),
;                         pk_bf16(st[kb][8 * sI + 4], st[kb][8 * sI + 5]), pk_bf16(st[kb][8 * sI + 6], st[kb][8 * sI + 7])};
;             const bf16x8 pf = __builtin_bit_cast(bf16x8, pw);
; #pragma unroll
;             for (int db = 0; db < 2; ++db) {
;                 const LAS unsigned char* vp = vb_ + (db * 32 + ql) * VROW + (kb * 32 + 16 * sI + 4 * hf) * 2;
;                 const u32x2 v0 = *(const LAS u32x2*)vp, v1 = *(const LAS u32x2*)(vp + 16);
;                 u32x4 vw = {v0[0], v0[1], v1[0], v1[1]};
;                 ot[db] = att_mma<MODE>(__builtin_bit_cast(bf16x8, vw), pf, ot[db]);
;             }
;         }
; }
; template <int MODE>
; __device__ __forceinline__ void attn_phase(const Args& a, bool do_ctx, LAS unsigned char* lds, const int wid_s) {
;     ...
;             ATT_WRITEV(vV, 1);
.Latt_wskip_e1:
	s_waitcnt vmcnt(0)
	ds_write2_b64 v251, v[128:129], v[130:131] offset1:2
	v_exp_f32_e32 v40, v40
	v_exp_f32_e32 v41, v41
	v_exp_f32_e32 v42, v42
	v_exp_f32_e32 v43, v43
	v_mfma_f32_32x32x16_bf16 v[16:31], v[222:225], v[152:155], v[16:31]
	v_exp_f32_e32 v44, v44
	v_exp_f32_e32 v45, v45
	v_exp_f32_e32 v46, v46
	v_exp_f32_e32 v47, v47
	v_mfma_f32_32x32x16_bf16 v[0:15], v[226:229], v[152:155], v[0:15]
	v_cvt_pk_bf16_f32 v48, v40, v41
	v_cvt_pk_bf16_f32 v49, v42, v43
	v_cvt_pk_bf16_f32 v50, v44, v45
	v_cvt_pk_bf16_f32 v51, v46, v47
	v_pk_add_f32 v[230:231], v[230:231], v[40:41]
	v_pk_add_f32 v[230:231], v[230:231], v[42:43]
	v_pk_add_f32 v[230:231], v[230:231], v[44:45]
	v_pk_add_f32 v[230:231], v[230:231], v[46:47]
	v_add_f32_e32 v230, v230, v231
	v_add_f32_e32 v167, v167, v230
	s_waitcnt lgkmcnt(0)
	v_mfma_f32_32x32x16_bf16 v[0:15], v[236:239], v[48:51], v[0:15]
	v_mfma_f32_32x32x16_bf16 v[16:31], a[0:3], v[48:51], v[16:31]

; template <int MODE>
; __device__ __forceinline__ void attn_pv(const LAS unsigned char* vb_, f32x16 (&st)[2], f32x16 (&ot)[2], float& mrun, float& lsum, const int ql, const int hf, const int lane) {
;     if (MODE != 1) {
;     float mx = max3f(st[0][0], st[1][0], st[0][1]), my = max3f(st[1][1], st[0][2], st[1][2]);
; #pragma unroll
;     for (int i = 3; i < 15; i += 2) { mx = max3f(mx, st[0][i], st[1][i]); my = max3f(my, st[0][i + 1], st[1][i + 1]); }
;     mx = max3f(mx, st[0][15], st[1][15]); mx = max3f(mx, my, my);
;     if (__builtin_amdgcn_ballot_w64(mx > mrun + 8.0f) != 0ull) {
;         mx = fmaxf(mx, shx32(mx, lane));
;         const float mnew = (mx > mrun + 8.0f) ? mx : mrun;
;         const float alpha = fexp2(mrun - mnew);
;         mrun = mnew; lsum *= alpha;
; #pragma unroll
;         for (int i = 0; i < 16; ++i) { ot[0][i] *= alpha; ot[1][i] *= alpha; }
;     }
;     float ps = 0.f;
; #pragma unroll
;     for (int kb = 0; kb < 2; ++kb)
; #pragma unroll
;         for (int i = 0; i < 16; ++i) { const float p = fexp2(st[kb][i] - mrun); st[kb][i] = p; ps += p; }
;     lsum += ps;
;     } else lsum += st[0][0];
; #pragma unroll
;     for (int kb = 0; kb < 2; ++kb)
; #pragma unroll
;         for (int sI = 0; sI < 2; ++sI) {
;             u32x4 pw = {pk_bf16(st[kb][8 * sI + 0], st[kb][8 * sI + 1]), pk_bf16(st[kb][8 * sI + 2], st[kb][8 * sI + 3]),
;                         pk_bf16(st[kb][8 * sI + 4], st[kb][8 * sI + 5]), pk_bf16(st[kb][8 * sI + 6], st[kb][8 * sI + 7])};
;             const bf16x8 pf = __builtin_bit_cast(bf16x8, pw);
; #pragma unroll
;             for (int db = 0; db < 2; ++db) {
;                 const LAS unsigned char* vp = vb_ + (db * 32 + ql) * VROW + (kb * 32 + 16 * sI + 4 * hf) * 2;
;                 const u32x2 v0 = *(const LAS u32x2*)vp, v1 = *(const LAS u32x2*)(vp + 16);
;                 u32x4 vw = {v0[0], v0[1], v1[0], v1[1]};
;                 ot[db] = att_mma<MODE>(__builtin_bit_cast(bf16x8, vw), pf, ot[db]);
;             }
;         }
; }
; template <int MODE>
; __device__ __forceinline__ void attn_phase(const Args& a, bool do_ctx, LAS unsigned char* lds, const int wid_s) {
;     ...
;             if (t + 3 < nkt) ATT_LOADK(kK, kR, t + 3);
;             if (t + 2 < nkt) ATT_LOADV(vV, t + 2);
;             if (t + 2 < nkt) attn_qk<MODE>(lds, qf, sa, ql, hf);
;             __builtin_amdgcn_sched_barrier(0);
.Latt_o_noK:
	s_and_b64 vcc, exec, s[8:9]
	s_cbranch_vccnz .Latt_o_tail
	global_load_dwordx4 v[128:131], v150, s[84:85] offset:256
	ds_read_b128 v[32:35], v165
	ds_read_b128 v[152:155], v165 offset:32
	ds_read_b128 v[36:39], v165 offset:6656
	ds_read_b128 v[206:209], v165 offset:6688
	ds_read_b128 v[210:213], v165 offset:64
	ds_read_b128 v[214:217], v165 offset:96
	ds_read_b128 v[218:221], v165 offset:6720
	ds_read_b128 v[222:225], v165 offset:6752
	ds_read_b128 v[176:179], v240 offset:35840
	ds_read_b128 v[180:183], v240 offset:40448
	ds_read_b128 v[184:187], v240 offset:35872
	ds_read_b128 v[188:191], v240 offset:40480
	ds_read_b128 v[192:195], v240 offset:35904
	ds_read_b128 v[196:199], v240 offset:40512
	ds_read_b128 v[172:175], v240 offset:35936
	v_max3_f32 v156, v80, v64, v81
	v_max3_f32 v157, v65, v82, v66
	v_max3_f32 v156, v156, v83, v67
	v_max3_f32 v157, v157, v84, v68
	v_max3_f32 v156, v156, v85, v69
	v_max3_f32 v157, v157, v86, v70
	v_max3_f32 v156, v156, v87, v71
	v_max3_f32 v157, v157, v88, v72
	v_max3_f32 v156, v156, v89, v73
	v_max3_f32 v157, v157, v90, v74
	v_max3_f32 v156, v156, v91, v75
	v_max3_f32 v157, v157, v92, v76
	v_max3_f32 v156, v156, v93, v77
	v_max3_f32 v157, v157, v94, v78
	v_max3_f32 v156, v156, v95, v79
	v_max3_f32 v157, v156, v157, v157
	v_add_f32_e32 v156, 0x41000000, v143
	v_cmp_gt_f32_e32 vcc, v157, v156
	s_cbranch_vccnz .Latt_o_nors_resc
.Latt_o_nors:
	s_cmp_eq_u32 s90, 0
	s_cbranch_scc1 .Latt_o_nors_gen
	v_exp_f32_e32 v80, v80
	v_exp_f32_e32 v81, v81
	v_exp_f32_e32 v82, v82
	v_exp_f32_e32 v83, v83
	v_exp_f32_e32 v84, v84
	v_exp_f32_e32 v85, v85
	v_exp_f32_e32 v86, v86
	v_exp_f32_e32 v87, v87
	s_waitcnt lgkmcnt(11)
	v_mfma_f32_32x32x16_bf16 v[48:63], v[32:35], v[112:115], 0
	v_cvt_pk_bf16_f32 v168, v80, v81
	v_cvt_pk_bf16_f32 v169, v82, v83
	v_cvt_pk_bf16_f32 v170, v84, v85
	v_cvt_pk_bf16_f32 v171, v86, v87
	v_mfma_f32_32x32x16_bf16 v[32:47], v[36:39], v[112:115], 0
	v_pk_add_f32 v[230:231], v[80:81], v[82:83]
	v_pk_add_f32 v[230:231], v[230:231], v[84:85]
	v_pk_add_f32 v[230:231], v[230:231], v[86:87]
	v_mfma_f32_32x32x16_bf16 v[48:63], v[152:155], v[96:99], v[48:63]
	v_mfma_f32_32x32x16_bf16 v[32:47], v[206:209], v[96:99], v[32:47]
	ds_read_b128 v[152:155], v165 offset:128
	ds_read_b128 v[206:209], v165 offset:160
	ds_read_b128 v[226:229], v165 offset:6784
	ds_read_b128 v[236:239], v165 offset:6816
	v_exp_f32_e32 v88, v88
	v_exp_f32_e32 v89, v89
	v_exp_f32_e32 v90, v90
	v_exp_f32_e32 v91, v91
	s_waitcnt lgkmcnt(11)
	v_mfma_f32_32x32x16_bf16 v[48:63], v[210:213], v[100:103], v[48:63]
	ds_read_b128 a[0:3], v240 offset:40544
	v_exp_f32_e32 v92, v92
	v_exp_f32_e32 v93, v93
	v_exp_f32_e32 v94, v94
	v_exp_f32_e32 v95, v95
	v_mfma_f32_32x32x16_bf16 v[32:47], v[218:221], v[100:103], v[32:47]
	v_mfma_f32_32x32x16_bf16 v[48:63], v[214:217], v[104:107], v[48:63]
	v_cvt_pk_bf16_f32 v80, v88, v89
	v_cvt_pk_bf16_f32 v81, v90, v91
	v_cvt_pk_bf16_f32 v82, v92, v93
	v_cvt_pk_bf16_f32 v83, v94, v95
	v_mfma_f32_32x32x16_bf16 v[32:47], v[222:225], v[104:107], v[32:47]
	s_waitcnt lgkmcnt(10)
	v_mfma_f32_32x32x16_bf16 v[0:15], v[176:179], v[168:171], v[0:15]
	v_pk_add_f32 v[230:231], v[230:231], v[88:89]
	v_pk_add_f32 v[230:231], v[230:231], v[90:91]
	v_pk_add_f32 v[230:231], v[230:231], v[92:93]
	v_pk_add_f32 v[230:231], v[230:231], v[94:95]
	v_mfma_f32_32x32x16_bf16 v[16:31], v[180:183], v[168:171], v[16:31]
	s_waitcnt lgkmcnt(1)
	v_mfma_f32_32x32x16_bf16 v[48:63], v[152:155], v[108:111], v[48:63]
	v_exp_f32_e32 v64, v64
	v_exp_f32_e32 v65, v65
	v_exp_f32_e32 v66, v66
	v_exp_f32_e32 v67, v67
	v_mfma_f32_32x32x16_bf16 v[0:15], v[184:187], v[80:83], v[0:15]
	v_exp_f32_e32 v68, v68
	v_exp_f32_e32 v69, v69
	v_exp_f32_e32 v70, v70
	v_exp_f32_e32 v71, v71
	v_mfma_f32_32x32x16_bf16 v[16:31], v[188:191], v[80:83], v[16:31]
	v_cvt_pk_bf16_f32 v168, v64, v65
	v_cvt_pk_bf16_f32 v169, v66, v67
	v_cvt_pk_bf16_f32 v170, v68, v69
	v_cvt_pk_bf16_f32 v171, v70, v71
	v_mfma_f32_32x32x16_bf16 v[32:47], v[226:229], v[108:111], v[32:47]
	v_pk_add_f32 v[230:231], v[230:231], v[64:65]
	v_pk_add_f32 v[230:231], v[230:231], v[66:67]
	v_pk_add_f32 v[230:231], v[230:231], v[68:69]
	v_pk_add_f32 v[230:231], v[230:231], v[70:71]
	v_mfma_f32_32x32x16_bf16 v[48:63], v[206:209], v[116:119], v[48:63]
	v_mfma_f32_32x32x16_bf16 v[32:47], v[236:239], v[116:119], v[32:47]
	s_andn2_b64 vcc, exec, s[10:11]
	s_cbranch_vccnz .Latt_wskip_o1
	s_waitcnt vmcnt(1)
	ds_write_b128 v162, v[120:123] offset:13312
	s_and_saveexec_b64 s[2:3], s[6:7]
	s_cbranch_execz .Latt_wk_o1
	s_waitcnt vmcnt(0)
	ds_write_b128 v164, v[124:127] offset:13440

; #define LAS __attribute__((address_space(3)))
; __device__ __forceinline__ unsigned pk_bf16(float lo, float hi) { unsigned r; asm("v_cvt_pk_bf16_f32 %0, %1, %2" : "=v"(r) : "v"(lo), "v"(hi)); return r; }
; __device__ __forceinline__ float fexp2(float x) { return __builtin_amdgcn_exp2f(x); }
; #define ATT_WRITEV(rv, buf) do { LAS u32x2* p_ = (LAS u32x2*)(ldsv + (buf) * VBUF + svt); u32x2 lo_ = {rv[0], rv[1]}, hi_ = {rv[2], rv[3]}; p_[0] = lo_; p_[1] = hi_; } while (0)
; template <int MODE>
; __device__ __forceinline__ void attn_pv(const LAS unsigned char* vb_, f32x16 (&st)[2], f32x16 (&ot)[2], float& mrun, float& lsum, const int ql, const int hf, const int lane) {
;     ...
;     float ps = 0.f;
; #pragma unroll
;     for (int kb = 0; kb < 2; ++kb)
; #pragma unroll
;         for (int i = 0; i < 16; ++i) { const float p = fexp2(st[kb][i] - mrun); st[kb][i] = p; ps += p; }
;     lsum += ps;
;     } else lsum += st[0][0];
; #pragma unroll
;     for (int kb = 0; kb < 2; ++kb)
; #pragma unroll
;         for (int sI = 0; sI < 2; ++sI) {
;             u32x4 pw = {pk_bf16(st[kb][8 * sI + 0], st[kb][8 * sI + 1]), pk_bf16(st[kb][8 * sI + 2], st[kb][8 * sI + 3]),
;                         pk_bf16(st[kb][8 * sI + 4], st[kb][8 * sI + 5]), pk_bf16(st[kb][8 * sI + 6], st[kb][8 * sI + 7])};
;             const bf16x8 pf = __builtin_bit_cast(bf16x8, pw);
; #pragma unroll
;             for (int db = 0; db < 2; ++db) {
;                 const LAS unsigned char* vp = vb_ + (db * 32 + ql) * VROW + (kb * 32 + 16 * sI + 4 * hf) * 2;
;                 const u32x2 v0 = *(const LAS u32x2*)vp, v1 = *(const LAS u32x2*)(vp + 16);
;                 u32x4 vw = {v0[0], v0[1], v1[0], v1[1]};
;                 ot[db] = att_mma<MODE>(__builtin_bit_cast(bf16x8, vw), pf, ot[db]);
;             }
;         }
; }
; template <int MODE>
; __device__ __forceinline__ void attn_phase(const Args& a, bool do_ctx, LAS unsigned char* lds, const int wid_s) {
;     ...
;             if (t + 2 < nkt) ATT_WRITEV(vV, 0);
.Latt_wskip_o1:
	s_waitcnt vmcnt(0)
	ds_write2_b64 v141, v[128:129], v[130:131] offset1:2
	v_exp_f32_e32 v72, v72
	v_exp_f32_e32 v73, v73
	v_exp_f32_e32 v74, v74
	v_exp_f32_e32 v75, v75
	v_mfma_f32_32x32x16_bf16 v[0:15], v[192:195], v[168:171], v[0:15]
	v_exp_f32_e32 v76, v76
	v_exp_f32_e32 v77, v77
	v_exp_f32_e32 v78, v78
	v_exp_f32_e32 v79, v79
	v_mfma_f32_32x32x16_bf16 v[16:31], v[196:199], v[168:171], v[16:31]
	v_cvt_pk_bf16_f32 v80, v72, v73
	v_cvt_pk_bf16_f32 v81, v74, v75
	v_cvt_pk_bf16_f32 v82, v76, v77
	v_cvt_pk_bf16_f32 v83, v78, v79
	v_pk_add_f32 v[230:231], v[230:231], v[72:73]
	v_pk_add_f32 v[230:231], v[230:231], v[74:75]
	v_pk_add_f32 v[230:231], v[230:231], v[76:77]
	v_pk_add_f32 v[230:231], v[230:231], v[78:79]
	v_add_f32_e32 v230, v230, v231
	v_add_f32_e32 v167, v167, v230
	s_waitcnt lgkmcnt(0)
	v_mfma_f32_32x32x16_bf16 v[0:15], v[172:175], v[80:83], v[0:15]
	v_mfma_f32_32x32x16_bf16 v[16:31], a[0:3], v[80:83], v[16:31]

; #define LAS __attribute__((address_space(3)))
; __device__ __forceinline__ float shx32(float v, int lane) { return __int_as_float(__builtin_amdgcn_ds_bpermute((lane ^ 32) << 2, __float_as_int(v))); }
; __device__ __forceinline__ unsigned pk_bf16(float lo, float hi) { unsigned r; asm("v_cvt_pk_bf16_f32 %0, %1, %2" : "=v"(r) : "v"(lo), "v"(hi)); return r; }
; template <int MODE>
; __device__ __forceinline__ void attn_pv(const LAS unsigned char* vb_, f32x16 (&st)[2], f32x16 (&ot)[2], float& mrun, float& lsum, const int ql, const int hf, const int lane) {
;     if (MODE != 1) {
;     float mx = max3f(st[0][0], st[1][0], st[0][1]), my = max3f(st[1][1], st[0][2], st[1][2]);
; #pragma unroll
;     for (int i = 3; i < 15; i += 2) { mx = max3f(mx, st[0][i], st[1][i]); my = max3f(my, st[0][i + 1], st[1][i + 1]); }
;     mx = max3f(mx, st[0][15], st[1][15]); mx = max3f(mx, my, my);
;     if (__builtin_amdgcn_ballot_w64(mx > mrun + 8.0f) != 0ull) {
;         mx = fmaxf(mx, shx32(mx, lane));
;         const float mnew = (mx > mrun + 8.0f) ? mx : mrun;
;         const float alpha = fexp2(mrun - mnew);
;         mrun = mnew; lsum *= alpha;
; #pragma unroll
;         for (int i = 0; i < 16; ++i) { ot[0][i] *= alpha; ot[1][i] *= alpha; }
;     }
;     float ps = 0.f;
; #pragma unroll
;     for (int kb = 0; kb < 2; ++kb)
; #pragma unroll
;         for (int i = 0; i < 16; ++i) { const float p = fexp2(st[kb][i] - mrun); st[kb][i] = p; ps += p; }
;     lsum += ps;
;     } else lsum += st[0][0];
; #pragma unroll
;     for (int kb = 0; kb < 2; ++kb)
; #pragma unroll
;         for (int sI = 0; sI < 2; ++sI) {
;             u32x4 pw = {pk_bf16(st[kb][8 * sI + 0], st[kb][8 * sI + 1]), pk_bf16(st[kb][8 * sI + 2], st[kb][8 * sI + 3]),
;                         pk_bf16(st[kb][8 * sI + 4], st[kb][8 * sI + 5]), pk_bf16(st[kb][8 * sI + 6], st[kb][8 * sI + 7])};
;             const bf16x8 pf = __builtin_bit_cast(bf16x8, pw);
; #pragma unroll
;             for (int db = 0; db < 2; ++db) {
;                 const LAS unsigned char* vp = vb_ + (db * 32 + ql) * VROW + (kb * 32 + 16 * sI + 4 * hf) * 2;
;                 const u32x2 v0 = *(const LAS u32x2*)vp, v1 = *(const LAS u32x2*)(vp + 16);
;                 u32x4 vw = {v0[0], v0[1], v1[0], v1[1]};
;                 ot[db] = att_mma<MODE>(__builtin_bit_cast(bf16x8, vw), pf, ot[db]);
;             }
;         }
; }
.Latt_o_tail:
	ds_read_b128 v[176:179], v240 offset:35840
	ds_read_b128 v[180:183], v240 offset:40448
	ds_read_b128 v[184:187], v240 offset:35872
	ds_read_b128 v[188:191], v240 offset:40480
	ds_read_b128 v[192:195], v240 offset:35904
	ds_read_b128 v[196:199], v240 offset:40512
	ds_read_b128 v[172:175], v240 offset:35936
	ds_read_b128 a[0:3], v240 offset:40544
	v_max3_f32 v156, v80, v64, v81
	v_max3_f32 v157, v65, v82, v66
	v_max3_f32 v156, v156, v83, v67
	v_max3_f32 v157, v157, v84, v68
	v_max3_f32 v156, v156, v85, v69
	v_max3_f32 v157, v157, v86, v70
	v_max3_f32 v156, v156, v87, v71
	v_max3_f32 v157, v157, v88, v72
	v_max3_f32 v156, v156, v89, v73
	v_max3_f32 v157, v157, v90, v74
	v_max3_f32 v156, v156, v91, v75
	v_max3_f32 v157, v157, v92, v76
	v_max3_f32 v156, v156, v93, v77
	v_max3_f32 v157, v157, v94, v78
	v_max3_f32 v156, v156, v95, v79
	v_max3_f32 v157, v156, v157, v157
	v_add_f32_e32 v156, 0x41000000, v143
	v_cmp_gt_f32_e32 vcc, v157, v156
	s_cbranch_vccnz .Latt_ot_nors_resc
.Latt_ot_nors:
	s_cmp_eq_u32 s90, 0
	s_cbranch_scc1 .Latt_ot_nors_gen
	v_exp_f32_e32 v80, v80
	v_exp_f32_e32 v81, v81
	v_exp_f32_e32 v82, v82
	v_exp_f32_e32 v83, v83
	v_exp_f32_e32 v84, v84
	v_exp_f32_e32 v85, v85
	v_exp_f32_e32 v86, v86
	v_exp_f32_e32 v87, v87
	v_cvt_pk_bf16_f32 v168, v80, v81
	v_cvt_pk_bf16_f32 v169, v82, v83
	v_cvt_pk_bf16_f32 v170, v84, v85
	v_cvt_pk_bf16_f32 v171, v86, v87
	v_pk_add_f32 v[230:231], v[80:81], v[82:83]
	v_pk_add_f32 v[230:231], v[230:231], v[84:85]
	v_pk_add_f32 v[230:231], v[230:231], v[86:87]
	v_exp_f32_e32 v88, v88
	v_exp_f32_e32 v89, v89
	v_exp_f32_e32 v90, v90
	v_exp_f32_e32 v91, v91
	s_waitcnt lgkmcnt(0)
	v_mfma_f32_32x32x16_bf16 v[0:15], v[176:179], v[168:171], v[0:15]
	v_exp_f32_e32 v92, v92
	v_exp_f32_e32 v93, v93
	v_exp_f32_e32 v94, v94
	v_exp_f32_e32 v95, v95
	v_mfma_f32_32x32x16_bf16 v[16:31], v[180:183], v[168:171], v[16:31]
	v_cvt_pk_bf16_f32 v80, v88, v89
	v_cvt_pk_bf16_f32 v81, v90, v91
	v_cvt_pk_bf16_f32 v82, v92, v93
	v_cvt_pk_bf16_f32 v83, v94, v95
	v_pk_add_f32 v[230:231], v[230:231], v[88:89]
	v_pk_add_f32 v[230:231], v[230:231], v[90:91]
	v_pk_add_f32 v[230:231], v[230:231], v[92:93]
	v_pk_add_f32 v[230:231], v[230:231], v[94:95]
	v_mfma_f32_32x32x16_bf16 v[0:15], v[184:187], v[80:83], v[0:15]
	v_exp_f32_e32 v64, v64
	v_exp_f32_e32 v65, v65
	v_exp_f32_e32 v66, v66
	v_exp_f32_e32 v67, v67
	v_mfma_f32_32x32x16_bf16 v[16:31], v[188:191], v[80:83], v[16:31]
	v_exp_f32_e32 v68, v68
	v_exp_f32_e32 v69, v69
	v_exp_f32_e32 v70, v70
	v_exp_f32_e32 v71, v71
	v_cvt_pk_bf16_f32 v168, v64, v65
	v_cvt_pk_bf16_f32 v169, v66, v67
	v_cvt_pk_bf16_f32 v170, v68, v69
	v_cvt_pk_bf16_f32 v171, v70, v71
	v_pk_add_f32 v[230:231], v[230:231], v[64:65]
	v_pk_add_f32 v[230:231], v[230:231], v[66:67]
	v_pk_add_f32 v[230:231], v[230:231], v[68:69]
	v_pk_add_f32 v[230:231], v[230:231], v[70:71]
	v_mfma_f32_32x32x16_bf16 v[0:15], v[192:195], v[168:171], v[0:15]
	v_exp_f32_e32 v72, v72
	v_exp_f32_e32 v73, v73
	v_exp_f32_e32 v74, v74
	v_exp_f32_e32 v75, v75
	v_mfma_f32_32x32x16_bf16 v[16:31], v[196:199], v[168:171], v[16:31]
	v_exp_f32_e32 v76, v76
	v_exp_f32_e32 v77, v77
	v_exp_f32_e32 v78, v78
	v_exp_f32_e32 v79, v79
	v_cvt_pk_bf16_f32 v80, v72, v73
	v_cvt_pk_bf16_f32 v81, v74, v75
	v_cvt_pk_bf16_f32 v82, v76, v77
	v_cvt_pk_bf16_f32 v83, v78, v79
	v_pk_add_f32 v[230:231], v[230:231], v[72:73]
	v_pk_add_f32 v[230:231], v[230:231], v[74:75]
	v_pk_add_f32 v[230:231], v[230:231], v[76:77]
	v_pk_add_f32 v[230:231], v[230:231], v[78:79]
	v_add_f32_e32 v230, v230, v231
	v_add_f32_e32 v167, v167, v230
	v_mfma_f32_32x32x16_bf16 v[0:15], v[172:175], v[80:83], v[0:15]
	v_mfma_f32_32x32x16_bf16 v[16:31], a[0:3], v[80:83], v[16:31]

; #define LAS __attribute__((address_space(3)))
; __device__ __forceinline__ float shx32(float v, int lane) { return __int_as_float(__builtin_amdgcn_ds_bpermute((lane ^ 32) << 2, __float_as_int(v))); }
; __device__ __forceinline__ unsigned pk_bf16(float lo, float hi) { unsigned r; asm("v_cvt_pk_bf16_f32 %0, %1, %2" : "=v"(r) : "v"(lo), "v"(hi)); return r; }
; template <int MODE>
; __device__ __forceinline__ void attn_pv(const LAS unsigned char* vb_, f32x16 (&st)[2], f32x16 (&ot)[2], float& mrun, float& lsum, const int ql, const int hf, const int lane) {
;     if (MODE != 1) {
;     float mx = max3f(st[0][0], st[1][0], st[0][1]), my = max3f(st[1][1], st[0][2], st[1][2]);
; #pragma unroll
;     for (int i = 3; i < 15; i += 2) { mx = max3f(mx, st[0][i], st[1][i]); my = max3f(my, st[0][i + 1], st[1][i + 1]); }
;     mx = max3f(mx, st[0][15], st[1][15]); mx = max3f(mx, my, my);
;     if (__builtin_amdgcn_ballot_w64(mx > mrun + 8.0f) != 0ull) {
;         mx = fmaxf(mx, shx32(mx, lane));
;         const float mnew = (mx > mrun + 8.0f) ? mx : mrun;
;         const float alpha = fexp2(mrun - mnew);
;         mrun = mnew; lsum *= alpha;
; #pragma unroll
;         for (int i = 0; i < 16; ++i) { ot[0][i] *= alpha; ot[1][i] *= alpha; }
;     }
;     float ps = 0.f;
; #pragma unroll
;     for (int kb = 0; kb < 2; ++kb)
; #pragma unroll
;         for (int i = 0; i < 16; ++i) { const float p = fexp2(st[kb][i] - mrun); st[kb][i] = p; ps += p; }
;     lsum += ps;
;     } else lsum += st[0][0];
; #pragma unroll
;     for (int kb = 0; kb < 2; ++kb)
; #pragma unroll
;         for (int sI = 0; sI < 2; ++sI) {
;             u32x4 pw = {pk_bf16(st[kb][8 * sI + 0], st[kb][8 * sI + 1]), pk_bf16(st[kb][8 * sI + 2], st[kb][8 * sI + 3]),
;                         pk_bf16(st[kb][8 * sI + 4], st[kb][8 * sI + 5]), pk_bf16(st[kb][8 * sI + 6], st[kb][8 * sI + 7])};
;             const bf16x8 pf = __builtin_bit_cast(bf16x8, pw);
; #pragma unroll
;             for (int db = 0; db < 2; ++db) {
;                 const LAS unsigned char* vp = vb_ + (db * 32 + ql) * VROW + (kb * 32 + 16 * sI + 4 * hf) * 2;
;                 const u32x2 v0 = *(const LAS u32x2*)vp, v1 = *(const LAS u32x2*)(vp + 16);
;                 u32x4 vw = {v0[0], v0[1], v1[0], v1[1]};
;                 ot[db] = att_mma<MODE>(__builtin_bit_cast(bf16x8, vw), pf, ot[db]);
;             }
;         }
; }
.LBB0_456:
	s_and_b64 vcc, exec, s[8:9]
	s_cbranch_vccnz .LBB0_434
	s_waitcnt vmcnt(0)
	ds_write2_b64 v141, v[128:129], v[130:131] offset1:2
	s_branch .LBB0_434
.Latt_e_nors_resc:
	ds_bpermute_b32 v231, v163, v157
	v_max_f32_e32 v157, v157, v157
	s_waitcnt lgkmcnt(0)
	v_max_f32_e32 v231, v231, v231
	v_max_f32_e32 v157, v157, v231
	v_cmp_gt_f32_e32 vcc, v157, v156
	s_nop 1
	v_cndmask_b32_e32 v157, v143, v157, vcc
	v_add_f32_e32 v231, 0x41400000, v157
	s_mov_b32 s2, 0x41a00000
	v_cmp_le_f32_e64 vcc, |v231|, s2
	s_nop 1
	v_cndmask_b32_e32 v157, v157, v201, vcc
	v_sub_f32_e32 v143, v143, v157
	v_exp_f32_e32 v156, v143
	v_mov_b32_e32 v143, v157
	v_mul_f32_e32 v167, v167, v156
	v_pk_mul_f32 v[14:15], v[14:15], v[156:157] op_sel_hi:[1,0]
	v_pk_mul_f32 v[12:13], v[12:13], v[156:157] op_sel_hi:[1,0]
	v_pk_mul_f32 v[10:11], v[10:11], v[156:157] op_sel_hi:[1,0]
	v_pk_mul_f32 v[8:9], v[8:9], v[156:157] op_sel_hi:[1,0]
	v_pk_mul_f32 v[6:7], v[6:7], v[156:157] op_sel_hi:[1,0]
	v_pk_mul_f32 v[4:5], v[4:5], v[156:157] op_sel_hi:[1,0]
	v_pk_mul_f32 v[2:3], v[2:3], v[156:157] op_sel_hi:[1,0]
	v_pk_mul_f32 v[0:1], v[0:1], v[156:157] op_sel_hi:[1,0]
	v_pk_mul_f32 v[30:31], v[30:31], v[156:157] op_sel_hi:[1,0]
	v_pk_mul_f32 v[28:29], v[28:29], v[156:157] op_sel_hi:[1,0]
	v_pk_mul_f32 v[26:27], v[26:27], v[156:157] op_sel_hi:[1,0]
	v_pk_mul_f32 v[24:25], v[24:25], v[156:157] op_sel_hi:[1,0]
	v_pk_mul_f32 v[22:23], v[22:23], v[156:157] op_sel_hi:[1,0]
	v_pk_mul_f32 v[20:21], v[20:21], v[156:157] op_sel_hi:[1,0]
	v_pk_mul_f32 v[18:19], v[18:19], v[156:157] op_sel_hi:[1,0]
	v_pk_mul_f32 v[16:17], v[16:17], v[156:157] op_sel_hi:[1,0]
	v_cmp_neq_f32_e32 vcc, 0, v143
	s_nop 1
	s_cmp_eq_u64 vcc, 0
	s_cselect_b32 s90, 1, 0
	s_branch .Latt_e_nors
.Latt_e_nors_gen:
	v_sub_f32_e32 v48, v48, v143
	v_sub_f32_e32 v49, v49, v143
	v_sub_f32_e32 v50, v50, v143
	v_sub_f32_e32 v51, v51, v143
	v_sub_f32_e32 v52, v52, v143
	v_sub_f32_e32 v53, v53, v143
	v_sub_f32_e32 v54, v54, v143
	v_sub_f32_e32 v55, v55, v143
	v_exp_f32_e32 v48, v48
	v_exp_f32_e32 v49, v49
	v_exp_f32_e32 v50, v50
	v_exp_f32_e32 v51, v51
	v_exp_f32_e32 v52, v52
	v_exp_f32_e32 v53, v53
	v_exp_f32_e32 v54, v54
	v_exp_f32_e32 v55, v55
	s_waitcnt lgkmcnt(11)
	v_mfma_f32_32x32x16_bf16 v[80:95], v[64:67], v[112:115], 0
	v_cvt_pk_bf16_f32 v152, v48, v49
	v_cvt_pk_bf16_f32 v153, v50, v51
	v_cvt_pk_bf16_f32 v154, v52, v53
	v_cvt_pk_bf16_f32 v155, v54, v55
	v_mfma_f32_32x32x16_bf16 v[64:79], v[68:71], v[112:115], 0
	v_pk_add_f32 v[230:231], v[48:49], v[50:51]
	v_pk_add_f32 v[230:231], v[230:231], v[52:53]
	v_pk_add_f32 v[230:231], v[230:231], v[54:55]
	v_mfma_f32_32x32x16_bf16 v[80:95], v[168:171], v[96:99], v[80:95]
	v_sub_f32_e32 v56, v56, v143
	v_sub_f32_e32 v57, v57, v143
	v_sub_f32_e32 v58, v58, v143
	v_sub_f32_e32 v59, v59, v143
	v_sub_f32_e32 v60, v60, v143
	v_sub_f32_e32 v61, v61, v143
	v_sub_f32_e32 v62, v62, v143
	v_sub_f32_e32 v63, v63, v143
	v_mfma_f32_32x32x16_bf16 v[64:79], v[172:175], v[96:99], v[64:79]
	ds_read_b128 v[168:171], v165 offset:13440
	ds_read_b128 v[172:175], v165 offset:13472
	ds_read_b128 v[192:195], v165 offset:20096
	ds_read_b128 v[196:199], v165 offset:20128
	v_exp_f32_e32 v56, v56
	v_exp_f32_e32 v57, v57
	v_exp_f32_e32 v58, v58
	v_exp_f32_e32 v59, v59
	s_waitcnt lgkmcnt(11)
	v_mfma_f32_32x32x16_bf16 v[80:95], v[176:179], v[100:103], v[80:95]
	ds_read_b128 a[0:3], v240 offset:31328
	v_exp_f32_e32 v60, v60
	v_exp_f32_e32 v61, v61
	v_exp_f32_e32 v62, v62
	v_exp_f32_e32 v63, v63
	v_mfma_f32_32x32x16_bf16 v[64:79], v[184:187], v[100:103], v[64:79]
	v_mfma_f32_32x32x16_bf16 v[80:95], v[180:183], v[104:107], v[80:95]
	v_cvt_pk_bf16_f32 v48, v56, v57
	v_cvt_pk_bf16_f32 v49, v58, v59
	v_cvt_pk_bf16_f32 v50, v60, v61
	v_cvt_pk_bf16_f32 v51, v62, v63
	v_mfma_f32_32x32x16_bf16 v[64:79], v[188:191], v[104:107], v[64:79]
	s_waitcnt lgkmcnt(10)
	v_mfma_f32_32x32x16_bf16 v[16:31], v[206:209], v[152:155], v[16:31]
	v_pk_add_f32 v[230:231], v[230:231], v[56:57]
	v_pk_add_f32 v[230:231], v[230:231], v[58:59]
	v_pk_add_f32 v[230:231], v[230:231], v[60:61]
	v_pk_add_f32 v[230:231], v[230:231], v[62:63]
	v_mfma_f32_32x32x16_bf16 v[0:15], v[210:213], v[152:155], v[0:15]
	v_sub_f32_e32 v32, v32, v143
	v_sub_f32_e32 v33, v33, v143
	v_sub_f32_e32 v34, v34, v143
	v_sub_f32_e32 v35, v35, v143
	v_sub_f32_e32 v36, v36, v143
	v_sub_f32_e32 v37, v37, v143
	v_sub_f32_e32 v38, v38, v143
	v_sub_f32_e32 v39, v39, v143
	s_waitcnt lgkmcnt(1)
	v_mfma_f32_32x32x16_bf16 v[80:95], v[168:171], v[108:111], v[80:95]
	v_exp_f32_e32 v32, v32
	v_exp_f32_e32 v33, v33
	v_exp_f32_e32 v34, v34
	v_exp_f32_e32 v35, v35
	v_mfma_f32_32x32x16_bf16 v[16:31], v[214:217], v[48:51], v[16:31]
	v_exp_f32_e32 v36, v36
	v_exp_f32_e32 v37, v37
	v_exp_f32_e32 v38, v38
	v_exp_f32_e32 v39, v39
	v_mfma_f32_32x32x16_bf16 v[0:15], v[218:221], v[48:51], v[0:15]
	v_cvt_pk_bf16_f32 v152, v32, v33
	v_cvt_pk_bf16_f32 v153, v34, v35
	v_cvt_pk_bf16_f32 v154, v36, v37
	v_cvt_pk_bf16_f32 v155, v38, v39
	v_mfma_f32_32x32x16_bf16 v[64:79], v[192:195], v[108:111], v[64:79]
	v_pk_add_f32 v[230:231], v[230:231], v[32:33]
	v_pk_add_f32 v[230:231], v[230:231], v[34:35]
	v_pk_add_f32 v[230:231], v[230:231], v[36:37]
	v_pk_add_f32 v[230:231], v[230:231], v[38:39]
	v_mfma_f32_32x32x16_bf16 v[80:95], v[172:175], v[116:119], v[80:95]
	v_sub_f32_e32 v40, v40, v143
	v_sub_f32_e32 v41, v41, v143
	v_sub_f32_e32 v42, v42, v143
	v_sub_f32_e32 v43, v43, v143
	v_sub_f32_e32 v44, v44, v143
	v_sub_f32_e32 v45, v45, v143
	v_sub_f32_e32 v46, v46, v143
	v_sub_f32_e32 v47, v47, v143
	v_mfma_f32_32x32x16_bf16 v[64:79], v[196:199], v[116:119], v[64:79]
	s_andn2_b64 vcc, exec, s[10:11]
	s_cbranch_vccnz .Latt_wskip_e2
	s_waitcnt vmcnt(2)
	ds_write_b128 v162, v[120:123]
	s_and_saveexec_b64 s[2:3], s[6:7]
	s_cbranch_execz .Latt_wk_e2
	s_waitcnt vmcnt(1)
	ds_write_b128 v164, v[124:127] offset:128

; #define LAS __attribute__((address_space(3)))
; __device__ __forceinline__ unsigned pk_bf16(float lo, float hi) { unsigned r; asm("v_cvt_pk_bf16_f32 %0, %1, %2" : "=v"(r) : "v"(lo), "v"(hi)); return r; }
; __device__ __forceinline__ float fexp2(float x) { return __builtin_amdgcn_exp2f(x); }
; #define ATT_WRITEK(rk, rr, buf) do { LAS unsigned char* nb_ = lds + (buf) * KBUF; *(LAS u32x4*)(nb_ + skn) = rk; if (tid < 256) *(LAS u32x4*)(nb_ + skr) = rr; } while (0)
; #define ATT_WRITEV(rv, buf) do { LAS u32x2* p_ = (LAS u32x2*)(ldsv + (buf) * VBUF + svt); u32x2 lo_ = {rv[0], rv[1]}, hi_ = {rv[2], rv[3]}; p_[0] = lo_; p_[1] = hi_; } while (0)
; template <int MODE>
; __device__ __forceinline__ void attn_pv(const LAS unsigned char* vb_, f32x16 (&st)[2], f32x16 (&ot)[2], float& mrun, float& lsum, const int ql, const int hf, const int lane) {
;     ...
;     float ps = 0.f;
; #pragma unroll
;     for (int kb = 0; kb < 2; ++kb)
; #pragma unroll
;         for (int i = 0; i < 16; ++i) { const float p = fexp2(st[kb][i] - mrun); st[kb][i] = p; ps += p; }
;     lsum += ps;
;     } else lsum += st[0][0];
; #pragma unroll
;     for (int kb = 0; kb < 2; ++kb)
; #pragma unroll
;         for (int sI = 0; sI < 2; ++sI) {
;             u32x4 pw = {pk_bf16(st[kb][8 * sI + 0], st[kb][8 * sI + 1]), pk_bf16(st[kb][8 * sI + 2], st[kb][8 * sI + 3]),
;                         pk_bf16(st[kb][8 * sI + 4], st[kb][8 * sI + 5]), pk_bf16(st[kb][8 * sI + 6], st[kb][8 * sI + 7])};
;             const bf16x8 pf = __builtin_bit_cast(bf16x8, pw);
; #pragma unroll
;             for (int db = 0; db < 2; ++db) {
;                 const LAS unsigned char* vp = vb_ + (db * 32 + ql) * VROW + (kb * 32 + 16 * sI + 4 * hf) * 2;
;                 const u32x2 v0 = *(const LAS u32x2*)vp, v1 = *(const LAS u32x2*)(vp + 16);
;                 u32x4 vw = {v0[0], v0[1], v1[0], v1[1]};
;                 ot[db] = att_mma<MODE>(__builtin_bit_cast(bf16x8, vw), pf, ot[db]);
;             }
;         }
; }
; template <int MODE>
; __device__ __forceinline__ void attn_phase(const Args& a, bool do_ctx, LAS unsigned char* lds, const int wid_s) {
;     ...
;             if (t + 2 < nkt) ATT_WRITEK(kK, kR, 0);
;             ATT_WRITEV(vV, 1);
.Latt_wskip_e2:
	s_waitcnt vmcnt(0)
	ds_write2_b64 v251, v[128:129], v[130:131] offset1:2
	v_exp_f32_e32 v40, v40
	v_exp_f32_e32 v41, v41
	v_exp_f32_e32 v42, v42
	v_exp_f32_e32 v43, v43
	v_mfma_f32_32x32x16_bf16 v[16:31], v[222:225], v[152:155], v[16:31]
	v_exp_f32_e32 v44, v44
	v_exp_f32_e32 v45, v45
	v_exp_f32_e32 v46, v46
	v_exp_f32_e32 v47, v47
	v_mfma_f32_32x32x16_bf16 v[0:15], v[226:229], v[152:155], v[0:15]
	v_cvt_pk_bf16_f32 v48, v40, v41
	v_cvt_pk_bf16_f32 v49, v42, v43
	v_cvt_pk_bf16_f32 v50, v44, v45
	v_cvt_pk_bf16_f32 v51, v46, v47
	v_pk_add_f32 v[230:231], v[230:231], v[40:41]
	v_pk_add_f32 v[230:231], v[230:231], v[42:43]
	v_pk_add_f32 v[230:231], v[230:231], v[44:45]
	v_pk_add_f32 v[230:231], v[230:231], v[46:47]
	v_add_f32_e32 v230, v230, v231
	v_add_f32_e32 v167, v167, v230
	s_waitcnt lgkmcnt(0)
	v_mfma_f32_32x32x16_bf16 v[0:15], v[236:239], v[48:51], v[0:15]
	v_mfma_f32_32x32x16_bf16 v[16:31], a[0:3], v[48:51], v[16:31]
	s_branch .Latt_e_nors_join

; #define LAS __attribute__((address_space(3)))
; __device__ __forceinline__ float shx32(float v, int lane) { return __int_as_float(__builtin_amdgcn_ds_bpermute((lane ^ 32) << 2, __float_as_int(v))); }
; __device__ __forceinline__ unsigned pk_bf16(float lo, float hi) { unsigned r; asm("v_cvt_pk_bf16_f32 %0, %1, %2" : "=v"(r) : "v"(lo), "v"(hi)); return r; }
; template <int MODE>
; __device__ __forceinline__ void attn_pv(const LAS unsigned char* vb_, f32x16 (&st)[2], f32x16 (&ot)[2], float& mrun, float& lsum, const int ql, const int hf, const int lane) {
;     if (MODE != 1) {
;     float mx = max3f(st[0][0], st[1][0], st[0][1]), my = max3f(st[1][1], st[0][2], st[1][2]);
; #pragma unroll
;     for (int i = 3; i < 15; i += 2) { mx = max3f(mx, st[0][i], st[1][i]); my = max3f(my, st[0][i + 1], st[1][i + 1]); }
;     mx = max3f(mx, st[0][15], st[1][15]); mx = max3f(mx, my, my);
;     if (__builtin_amdgcn_ballot_w64(mx > mrun + 8.0f) != 0ull) {
;         mx = fmaxf(mx, shx32(mx, lane));
;         const float mnew = (mx > mrun + 8.0f) ? mx : mrun;
;         const float alpha = fexp2(mrun - mnew);
;         mrun = mnew; lsum *= alpha;
; #pragma unroll
;         for (int i = 0; i < 16; ++i) { ot[0][i] *= alpha; ot[1][i] *= alpha; }
;     }
;     float ps = 0.f;
; #pragma unroll
;     for (int kb = 0; kb < 2; ++kb)
; #pragma unroll
;         for (int i = 0; i < 16; ++i) { const float p = fexp2(st[kb][i] - mrun); st[kb][i] = p; ps += p; }
;     lsum += ps;
;     } else lsum += st[0][0];
; #pragma unroll
;     for (int kb = 0; kb < 2; ++kb)
; #pragma unroll
;         for (int sI = 0; sI < 2; ++sI) {
;             u32x4 pw = {pk_bf16(st[kb][8 * sI + 0], st[kb][8 * sI + 1]), pk_bf16(st[kb][8 * sI + 2], st[kb][8 * sI + 3]),
;                         pk_bf16(st[kb][8 * sI + 4], st[kb][8 * sI + 5]), pk_bf16(st[kb][8 * sI + 6], st[kb][8 * sI + 7])};
;             const bf16x8 pf = __builtin_bit_cast(bf16x8, pw);
; #pragma unroll
;             for (int db = 0; db < 2; ++db) {
;                 const LAS unsigned char* vp = vb_ + (db * 32 + ql) * VROW + (kb * 32 + 16 * sI + 4 * hf) * 2;
;                 const u32x2 v0 = *(const LAS u32x2*)vp, v1 = *(const LAS u32x2*)(vp + 16);
;                 u32x4 vw = {v0[0], v0[1], v1[0], v1[1]};
;                 ot[db] = att_mma<MODE>(__builtin_bit_cast(bf16x8, vw), pf, ot[db]);
;             }
;         }
; }
.Latt_o_nors_gen:
	v_sub_f32_e32 v80, v80, v143
	v_sub_f32_e32 v81, v81, v143
	v_sub_f32_e32 v82, v82, v143
	v_sub_f32_e32 v83, v83, v143
	v_sub_f32_e32 v84, v84, v143
	v_sub_f32_e32 v85, v85, v143
	v_sub_f32_e32 v86, v86, v143
	v_sub_f32_e32 v87, v87, v143
	v_exp_f32_e32 v80, v80
	v_exp_f32_e32 v81, v81
	v_exp_f32_e32 v82, v82
	v_exp_f32_e32 v83, v83
	v_exp_f32_e32 v84, v84
	v_exp_f32_e32 v85, v85
	v_exp_f32_e32 v86, v86
	v_exp_f32_e32 v87, v87
	s_waitcnt lgkmcnt(11)
	v_mfma_f32_32x32x16_bf16 v[48:63], v[32:35], v[112:115], 0
	v_cvt_pk_bf16_f32 v168, v80, v81
	v_cvt_pk_bf16_f32 v169, v82, v83
	v_cvt_pk_bf16_f32 v170, v84, v85
	v_cvt_pk_bf16_f32 v171, v86, v87
	v_mfma_f32_32x32x16_bf16 v[32:47], v[36:39], v[112:115], 0
	v_pk_add_f32 v[230:231], v[80:81], v[82:83]
	v_pk_add_f32 v[230:231], v[230:231], v[84:85]
	v_pk_add_f32 v[230:231], v[230:231], v[86:87]
	v_mfma_f32_32x32x16_bf16 v[48:63], v[152:155], v[96:99], v[48:63]
	v_sub_f32_e32 v88, v88, v143
	v_sub_f32_e32 v89, v89, v143
	v_sub_f32_e32 v90, v90, v143
	v_sub_f32_e32 v91, v91, v143
	v_sub_f32_e32 v92, v92, v143
	v_sub_f32_e32 v93, v93, v143
	v_sub_f32_e32 v94, v94, v143
	v_sub_f32_e32 v95, v95, v143
	v_mfma_f32_32x32x16_bf16 v[32:47], v[206:209], v[96:99], v[32:47]
	ds_read_b128 v[152:155], v165 offset:128
	ds_read_b128 v[206:209], v165 offset:160
	ds_read_b128 v[226:229], v165 offset:6784
	ds_read_b128 v[236:239], v165 offset:6816
	v_exp_f32_e32 v88, v88
	v_exp_f32_e32 v89, v89
	v_exp_f32_e32 v90, v90
	v_exp_f32_e32 v91, v91
	s_waitcnt lgkmcnt(11)
	v_mfma_f32_32x32x16_bf16 v[48:63], v[210:213], v[100:103], v[48:63]
	ds_read_b128 a[0:3], v240 offset:40544
	v_exp_f32_e32 v92, v92
	v_exp_f32_e32 v93, v93
	v_exp_f32_e32 v94, v94
	v_exp_f32_e32 v95, v95
	v_mfma_f32_32x32x16_bf16 v[32:47], v[218:221], v[100:103], v[32:47]
	v_mfma_f32_32x32x16_bf16 v[48:63], v[214:217], v[104:107], v[48:63]
	v_cvt_pk_bf16_f32 v80, v88, v89
	v_cvt_pk_bf16_f32 v81, v90, v91
	v_cvt_pk_bf16_f32 v82, v92, v93
	v_cvt_pk_bf16_f32 v83, v94, v95
	v_mfma_f32_32x32x16_bf16 v[32:47], v[222:225], v[104:107], v[32:47]
	s_waitcnt lgkmcnt(10)
	v_mfma_f32_32x32x16_bf16 v[0:15], v[176:179], v[168:171], v[0:15]
	v_pk_add_f32 v[230:231], v[230:231], v[88:89]
	v_pk_add_f32 v[230:231], v[230:231], v[90:91]
	v_pk_add_f32 v[230:231], v[230:231], v[92:93]
	v_pk_add_f32 v[230:231], v[230:231], v[94:95]
	v_mfma_f32_32x32x16_bf16 v[16:31], v[180:183], v[168:171], v[16:31]
	v_sub_f32_e32 v64, v64, v143
	v_sub_f32_e32 v65, v65, v143
	v_sub_f32_e32 v66, v66, v143
	v_sub_f32_e32 v67, v67, v143
	v_sub_f32_e32 v68, v68, v143
	v_sub_f32_e32 v69, v69, v143
	v_sub_f32_e32 v70, v70, v143
	v_sub_f32_e32 v71, v71, v143
	s_waitcnt lgkmcnt(1)
	v_mfma_f32_32x32x16_bf16 v[48:63], v[152:155], v[108:111], v[48:63]
	v_exp_f32_e32 v64, v64
	v_exp_f32_e32 v65, v65
	v_exp_f32_e32 v66, v66
	v_exp_f32_e32 v67, v67
	v_mfma_f32_32x32x16_bf16 v[0:15], v[184:187], v[80:83], v[0:15]
	v_exp_f32_e32 v68, v68
	v_exp_f32_e32 v69, v69
	v_exp_f32_e32 v70, v70
	v_exp_f32_e32 v71, v71
	v_mfma_f32_32x32x16_bf16 v[16:31], v[188:191], v[80:83], v[16:31]
	v_cvt_pk_bf16_f32 v168, v64, v65
	v_cvt_pk_bf16_f32 v169, v66, v67
	v_cvt_pk_bf16_f32 v170, v68, v69
	v_cvt_pk_bf16_f32 v171, v70, v71
	v_mfma_f32_32x32x16_bf16 v[32:47], v[226:229], v[108:111], v[32:47]
	v_pk_add_f32 v[230:231], v[230:231], v[64:65]
	v_pk_add_f32 v[230:231], v[230:231], v[66:67]
	v_pk_add_f32 v[230:231], v[230:231], v[68:69]
	v_pk_add_f32 v[230:231], v[230:231], v[70:71]
	v_mfma_f32_32x32x16_bf16 v[48:63], v[206:209], v[116:119], v[48:63]
	v_sub_f32_e32 v72, v72, v143
	v_sub_f32_e32 v73, v73, v143
	v_sub_f32_e32 v74, v74, v143
	v_sub_f32_e32 v75, v75, v143
	v_sub_f32_e32 v76, v76, v143
	v_sub_f32_e32 v77, v77, v143
	v_sub_f32_e32 v78, v78, v143
	v_sub_f32_e32 v79, v79, v143
	v_mfma_f32_32x32x16_bf16 v[32:47], v[236:239], v[116:119], v[32:47]
	s_andn2_b64 vcc, exec, s[10:11]
	s_cbranch_vccnz .Latt_wskip_o2
	s_waitcnt vmcnt(1)
	ds_write_b128 v162, v[120:123] offset:13312
	s_and_saveexec_b64 s[2:3], s[6:7]
	s_cbranch_execz .Latt_wk_o2
	s_waitcnt vmcnt(0)
	ds_write_b128 v164, v[124:127] offset:13440

; #define LAS __attribute__((address_space(3)))
; __device__ __forceinline__ unsigned pk_bf16(float lo, float hi) { unsigned r; asm("v_cvt_pk_bf16_f32 %0, %1, %2" : "=v"(r) : "v"(lo), "v"(hi)); return r; }
; __device__ __forceinline__ float fexp2(float x) { return __builtin_amdgcn_exp2f(x); }
; #define ATT_WRITEK(rk, rr, buf) do { LAS unsigned char* nb_ = lds + (buf) * KBUF; *(LAS u32x4*)(nb_ + skn) = rk; if (tid < 256) *(LAS u32x4*)(nb_ + skr) = rr; } while (0)
; #define ATT_WRITEV(rv, buf) do { LAS u32x2* p_ = (LAS u32x2*)(ldsv + (buf) * VBUF + svt); u32x2 lo_ = {rv[0], rv[1]}, hi_ = {rv[2], rv[3]}; p_[0] = lo_; p_[1] = hi_; } while (0)
; template <int MODE>
; __device__ __forceinline__ void attn_pv(const LAS unsigned char* vb_, f32x16 (&st)[2], f32x16 (&ot)[2], float& mrun, float& lsum, const int ql, const int hf, const int lane) {
;     ...
;     float ps = 0.f;
; #pragma unroll
;     for (int kb = 0; kb < 2; ++kb)
; #pragma unroll
;         for (int i = 0; i < 16; ++i) { const float p = fexp2(st[kb][i] - mrun); st[kb][i] = p; ps += p; }
;     lsum += ps;
;     } else lsum += st[0][0];
; #pragma unroll
;     for (int kb = 0; kb < 2; ++kb)
; #pragma unroll
;         for (int sI = 0; sI < 2; ++sI) {
;             u32x4 pw = {pk_bf16(st[kb][8 * sI + 0], st[kb][8 * sI + 1]), pk_bf16(st[kb][8 * sI + 2], st[kb][8 * sI + 3]),
;                         pk_bf16(st[kb][8 * sI + 4], st[kb][8 * sI + 5]), pk_bf16(st[kb][8 * sI + 6], st[kb][8 * sI + 7])};
;             const bf16x8 pf = __builtin_bit_cast(bf16x8, pw);
; #pragma unroll
;             for (int db = 0; db < 2; ++db) {
;                 const LAS unsigned char* vp = vb_ + (db * 32 + ql) * VROW + (kb * 32 + 16 * sI + 4 * hf) * 2;
;                 const u32x2 v0 = *(const LAS u32x2*)vp, v1 = *(const LAS u32x2*)(vp + 16);
;                 u32x4 vw = {v0[0], v0[1], v1[0], v1[1]};
;                 ot[db] = att_mma<MODE>(__builtin_bit_cast(bf16x8, vw), pf, ot[db]);
;             }
;         }
; }
; template <int MODE>
; __device__ __forceinline__ void attn_phase(const Args& a, bool do_ctx, LAS unsigned char* lds, const int wid_s) {
;     ...
;             if (t + 3 < nkt) ATT_WRITEK(kK, kR, 1);
;             if (t + 2 < nkt) ATT_WRITEV(vV, 0);
.Latt_wskip_o2:
	s_waitcnt vmcnt(0)
	ds_write2_b64 v141, v[128:129], v[130:131] offset1:2
	v_exp_f32_e32 v72, v72
	v_exp_f32_e32 v73, v73
	v_exp_f32_e32 v74, v74
	v_exp_f32_e32 v75, v75
	v_mfma_f32_32x32x16_bf16 v[0:15], v[192:195], v[168:171], v[0:15]
	v_exp_f32_e32 v76, v76
	v_exp_f32_e32 v77, v77
	v_exp_f32_e32 v78, v78
	v_exp_f32_e32 v79, v79
	v_mfma_f32_32x32x16_bf16 v[16:31], v[196:199], v[168:171], v[16:31]
	v_cvt_pk_bf16_f32 v80, v72, v73
	v_cvt_pk_bf16_f32 v81, v74, v75
	v_cvt_pk_bf16_f32 v82, v76, v77
	v_cvt_pk_bf16_f32 v83, v78, v79
	v_pk_add_f32 v[230:231], v[230:231], v[72:73]
	v_pk_add_f32 v[230:231], v[230:231], v[74:75]
	v_pk_add_f32 v[230:231], v[230:231], v[76:77]
	v_pk_add_f32 v[230:231], v[230:231], v[78:79]
	v_add_f32_e32 v230, v230, v231
	v_add_f32_e32 v167, v167, v230
	s_waitcnt lgkmcnt(0)
	v_mfma_f32_32x32x16_bf16 v[0:15], v[172:175], v[80:83], v[0:15]
	v_mfma_f32_32x32x16_bf16 v[16:31], a[0:3], v[80:83], v[16:31]
	s_branch .Latt_o_nors_join

; #define LAS __attribute__((address_space(3)))
; __device__ __forceinline__ unsigned pk_bf16(float lo, float hi) { unsigned r; asm("v_cvt_pk_bf16_f32 %0, %1, %2" : "=v"(r) : "v"(lo), "v"(hi)); return r; }
; __device__ __forceinline__ float fexp2(float x) { return __builtin_amdgcn_exp2f(x); }
; template <int MODE>
; __device__ __forceinline__ void attn_pv(const LAS unsigned char* vb_, f32x16 (&st)[2], f32x16 (&ot)[2], float& mrun, float& lsum, const int ql, const int hf, const int lane) {
;     ...
;     float ps = 0.f;
; #pragma unroll
;     for (int kb = 0; kb < 2; ++kb)
; #pragma unroll
;         for (int i = 0; i < 16; ++i) { const float p = fexp2(st[kb][i] - mrun); st[kb][i] = p; ps += p; }
;     lsum += ps;
;     } else lsum += st[0][0];
; #pragma unroll
;     for (int kb = 0; kb < 2; ++kb)
; #pragma unroll
;         for (int sI = 0; sI < 2; ++sI) {
;             u32x4 pw = {pk_bf16(st[kb][8 * sI + 0], st[kb][8 * sI + 1]), pk_bf16(st[kb][8 * sI + 2], st[kb][8 * sI + 3]),
;                         pk_bf16(st[kb][8 * sI + 4], st[kb][8 * sI + 5]), pk_bf16(st[kb][8 * sI + 6], st[kb][8 * sI + 7])};
;             const bf16x8 pf = __builtin_bit_cast(bf16x8, pw);
; #pragma unroll
;             for (int db = 0; db < 2; ++db) {
;                 const LAS unsigned char* vp = vb_ + (db * 32 + ql) * VROW + (kb * 32 + 16 * sI + 4 * hf) * 2;
;                 const u32x2 v0 = *(const LAS u32x2*)vp, v1 = *(const LAS u32x2*)(vp + 16);
;                 u32x4 vw = {v0[0], v0[1], v1[0], v1[1]};
;                 ot[db] = att_mma<MODE>(__builtin_bit_cast(bf16x8, vw), pf, ot[db]);
;             }
;         }
; }
.Latt_ot_nors_gen:
	v_sub_f32_e32 v80, v80, v143
	v_sub_f32_e32 v81, v81, v143
	v_sub_f32_e32 v82, v82, v143
	v_sub_f32_e32 v83, v83, v143
	v_sub_f32_e32 v84, v84, v143
	v_sub_f32_e32 v85, v85, v143
	v_sub_f32_e32 v86, v86, v143
	v_sub_f32_e32 v87, v87, v143
	v_exp_f32_e32 v80, v80
	v_exp_f32_e32 v81, v81
	v_exp_f32_e32 v82, v82
	v_exp_f32_e32 v83, v83
	v_exp_f32_e32 v84, v84
	v_exp_f32_e32 v85, v85
	v_exp_f32_e32 v86, v86
	v_exp_f32_e32 v87, v87
	v_cvt_pk_bf16_f32 v168, v80, v81
	v_cvt_pk_bf16_f32 v169, v82, v83
	v_cvt_pk_bf16_f32 v170, v84, v85
	v_cvt_pk_bf16_f32 v171, v86, v87
	v_pk_add_f32 v[230:231], v[80:81], v[82:83]
	v_pk_add_f32 v[230:231], v[230:231], v[84:85]
	v_pk_add_f32 v[230:231], v[230:231], v[86:87]
	v_sub_f32_e32 v88, v88, v143
	v_sub_f32_e32 v89, v89, v143
	v_sub_f32_e32 v90, v90, v143
	v_sub_f32_e32 v91, v91, v143
	v_sub_f32_e32 v92, v92, v143
	v_sub_f32_e32 v93, v93, v143
	v_sub_f32_e32 v94, v94, v143
	v_sub_f32_e32 v95, v95, v143
	v_exp_f32_e32 v88, v88
	v_exp_f32_e32 v89, v89
	v_exp_f32_e32 v90, v90
	v_exp_f32_e32 v91, v91
	s_waitcnt lgkmcnt(0)
	v_mfma_f32_32x32x16_bf16 v[0:15], v[176:179], v[168:171], v[0:15]
	v_exp_f32_e32 v92, v92
	v_exp_f32_e32 v93, v93
	v_exp_f32_e32 v94, v94
	v_exp_f32_e32 v95, v95
	v_mfma_f32_32x32x16_bf16 v[16:31], v[180:183], v[168:171], v[16:31]
	v_cvt_pk_bf16_f32 v80, v88, v89
	v_cvt_pk_bf16_f32 v81, v90, v91
	v_cvt_pk_bf16_f32 v82, v92, v93
	v_cvt_pk_bf16_f32 v83, v94, v95
	v_pk_add_f32 v[230:231], v[230:231], v[88:89]
	v_pk_add_f32 v[230:231], v[230:231], v[90:91]
	v_pk_add_f32 v[230:231], v[230:231], v[92:93]
	v_pk_add_f32 v[230:231], v[230:231], v[94:95]
	v_sub_f32_e32 v64, v64, v143
	v_sub_f32_e32 v65, v65, v143
	v_sub_f32_e32 v66, v66, v143
	v_sub_f32_e32 v67, v67, v143
	v_sub_f32_e32 v68, v68, v143
	v_sub_f32_e32 v69, v69, v143
	v_sub_f32_e32 v70, v70, v143
	v_sub_f32_e32 v71, v71, v143
	v_mfma_f32_32x32x16_bf16 v[0:15], v[184:187], v[80:83], v[0:15]
	v_exp_f32_e32 v64, v64
	v_exp_f32_e32 v65, v65
	v_exp_f32_e32 v66, v66
	v_exp_f32_e32 v67, v67
	v_mfma_f32_32x32x16_bf16 v[16:31], v[188:191], v[80:83], v[16:31]
	v_exp_f32_e32 v68, v68
	v_exp_f32_e32 v69, v69
	v_exp_f32_e32 v70, v70
	v_exp_f32_e32 v71, v71
	v_cvt_pk_bf16_f32 v168, v64, v65
	v_cvt_pk_bf16_f32 v169, v66, v67
	v_cvt_pk_bf16_f32 v170, v68, v69
	v_cvt_pk_bf16_f32 v171, v70, v71
	v_pk_add_f32 v[230:231], v[230:231], v[64:65]
	v_pk_add_f32 v[230:231], v[230:231], v[66:67]
	v_pk_add_f32 v[230:231], v[230:231], v[68:69]
	v_pk_add_f32 v[230:231], v[230:231], v[70:71]
	v_sub_f32_e32 v72, v72, v143
	v_sub_f32_e32 v73, v73, v143
	v_sub_f32_e32 v74, v74, v143
	v_sub_f32_e32 v75, v75, v143
	v_sub_f32_e32 v76, v76, v143
	v_sub_f32_e32 v77, v77, v143
	v_sub_f32_e32 v78, v78, v143
	v_sub_f32_e32 v79, v79, v143
	v_mfma_f32_32x32x16_bf16 v[0:15], v[192:195], v[168:171], v[0:15]
	v_exp_f32_e32 v72, v72
	v_exp_f32_e32 v73, v73
	v_exp_f32_e32 v74, v74
	v_exp_f32_e32 v75, v75
	v_mfma_f32_32x32x16_bf16 v[16:31], v[196:199], v[168:171], v[16:31]
	v_exp_f32_e32 v76, v76
	v_exp_f32_e32 v77, v77
	v_exp_f32_e32 v78, v78
	v_exp_f32_e32 v79, v79
	v_cvt_pk_bf16_f32 v80, v72, v73
	v_cvt_pk_bf16_f32 v81, v74, v75
	v_cvt_pk_bf16_f32 v82, v76, v77
	v_cvt_pk_bf16_f32 v83, v78, v79
	v_pk_add_f32 v[230:231], v[230:231], v[72:73]
	v_pk_add_f32 v[230:231], v[230:231], v[74:75]
	v_pk_add_f32 v[230:231], v[230:231], v[76:77]
	v_pk_add_f32 v[230:231], v[230:231], v[78:79]
	v_add_f32_e32 v230, v230, v231
	v_add_f32_e32 v167, v167, v230
	v_mfma_f32_32x32x16_bf16 v[0:15], v[172:175], v[80:83], v[0:15]
	v_mfma_f32_32x32x16_bf16 v[16:31], a[0:3], v[80:83], v[16:31]
	s_branch .Latt_ot_nors_join
